# attention H1: each K/V LDS-DMA piece issued after its stage's MFMA pair instead of before it
# speedup vs baseline: 1.0526x; 1.0050x over previous
; #define SBAR() __builtin_amdgcn_sched_barrier(0)
; template <int P> __device__ __forceinline__ void dma_piece(const DmaCtx& c) {
;   if constexpr (P < 3) __builtin_amdgcn_raw_ptr_buffer_load_lds(c.srd, (lds_u32_t*)(c.kd + (c.wid + 8 * P) * 1024), 16, c.koff[P], c.gk, 0, 0);
;   else __builtin_amdgcn_raw_ptr_buffer_load_lds(c.srd, (lds_u32_t*)(c.vd + (c.wid + 8 * (P - 3)) * 1024), 16, c.voff[P - 3], c.gv, 0, 0);
; }
; template <int D0> __device__ __forceinline__ void h1_stage(f32x16& pc0, f32x16& pc1, f32x16& pp0, f32x16& pp1, float alP, float& l_reg, SMState& st, bf16x8& pa0, bf16x8& pa1, bf16x8& pa2, bf16x8& pa3, ...
;   bf16x8 m0, m1, mq;
;   if constexpr (D0 < 10) kq_load<D0 + 2>(m0, m1, mq, Ks, qr, qlds, kb);
;   pc0 = __builtin_amdgcn_mfma_f32_32x32x16_bf16(b0, q, pc0, 0, 0, 0);
;   pc1 = __builtin_amdgcn_mfma_f32_32x32x16_bf16(b1, q, pc1, 0, 0, 0);
;   if constexpr (D0 >= 1 && D0 <= 5) dma_piece<D0 - 1>(dc);
;   SBAR(); fs_chunk<D0>(pp0, pp1, alP, l_reg, st, pa0, pa1, pa2, pa3); SBAR();
;   if constexpr (D0 < 11) h1_stage<D0 + 1>(pc0, pc1, pp0, pp1, alP, l_reg, st, pa0, pa1, pa2, pa3, n0, n1, nq, m0, m1, mq, Ks, qr, qlds, kb, dc);
; }
.Lattn_m2:
	v_xor_b32_e32 v112, 0x80000000, v191
	v_mov_b32_e32 v113, v112
	v_mov_b32_e32 v114, v112
	v_mov_b32_e32 v115, v112
	v_mov_b32_e32 v116, v112
	v_mov_b32_e32 v117, v112
	v_mov_b32_e32 v118, v112
	v_mov_b32_e32 v119, v112
	v_mov_b32_e32 v120, v112
	v_mov_b32_e32 v121, v112
	v_mov_b32_e32 v122, v112
	v_mov_b32_e32 v123, v112
	v_mov_b32_e32 v124, v112
	v_mov_b32_e32 v125, v112
	v_mov_b32_e32 v126, v112
	v_mov_b32_e32 v127, v112
	v_add_u32_e32 v224, s10, v199
	v_add_u32_e32 v225, s10, v200
	s_waitcnt lgkmcnt(1)
	v_mfma_f32_32x32x16_bf16 v[96:111], v[204:207], v[156:159], v[112:127]
	ds_read_b128 v[204:207], v224 offset:32768
	ds_read_b128 v[212:215], v224 offset:45056
	ds_read_b128 v[216:219], v225 offset:32768
	ds_read_b128 v[220:223], v225 offset:45056
	s_mul_i32 s11, s52, 0x6000
	s_add_i32 s53, s11, 0
	s_add_i32 s11, s51, 0xfffbe000
	s_waitcnt lgkmcnt(4)
	v_mfma_f32_32x32x16_bf16 v[112:127], v[208:211], v[156:159], v[112:127]
	v_exp_f32_e32 v226, v80
	v_exp_f32_e32 v227, v81
	v_exp_f32_e32 v228, v82
	v_exp_f32_e32 v229, v83
	v_add_u32_e32 v230, s10, v201
	s_add_i32 s10, s53, s69
	s_add_i32 m0, s10, 0x8000
	ds_read_b128 v[80:83], v230 offset:32768
	ds_read_b128 v[208:211], v230 offset:45056
	s_waitcnt lgkmcnt(5)
	v_mfma_f32_32x32x16_bf16 v[96:111], v[204:207], v[152:155], v[96:111]
	s_waitcnt lgkmcnt(4)
	v_mfma_f32_32x32x16_bf16 v[112:127], v[212:215], v[152:155], v[112:127]
	buffer_load_dwordx4 v194, s[28:31], s51 offen lds
	v_exp_f32_e32 v231, v84
	v_exp_f32_e32 v232, v85
	v_exp_f32_e32 v233, v86
	v_exp_f32_e32 v234, v87
	s_add_i32 m0, s10, 0xa000
	ds_read_b128 v[84:87], v203 offset:32896
	ds_read_b128 v[204:207], v203 offset:45184
	s_waitcnt lgkmcnt(5)
	v_mfma_f32_32x32x16_bf16 v[96:111], v[216:219], v[148:151], v[96:111]
	s_waitcnt lgkmcnt(4)
	v_mfma_f32_32x32x16_bf16 v[112:127], v[220:223], v[148:151], v[112:127]
	buffer_load_dwordx4 v195, s[28:31], s51 offen lds
	v_exp_f32_e32 v235, v88
	v_exp_f32_e32 v236, v89
	v_exp_f32_e32 v237, v90
	v_exp_f32_e32 v238, v91
	s_add_i32 m0, s10, 0xc000
	ds_read_b128 v[88:91], v224 offset:32896
	ds_read_b128 v[212:215], v224 offset:45184
	s_waitcnt lgkmcnt(5)
	v_mfma_f32_32x32x16_bf16 v[96:111], v[80:83], v[144:147], v[96:111]
	s_waitcnt lgkmcnt(4)
	v_mfma_f32_32x32x16_bf16 v[112:127], v[208:211], v[144:147], v[112:127]
	buffer_load_dwordx4 v196, s[28:31], s51 offen lds
	v_exp_f32_e32 v239, v92
	v_exp_f32_e32 v240, v93
	v_exp_f32_e32 v241, v94
	v_exp_f32_e32 v242, v95
	s_mov_b32 m0, s50
	ds_read_b128 v[80:83], v225 offset:32896
	ds_read_b128 v[92:95], v225 offset:45184
	s_waitcnt lgkmcnt(5)
	v_mfma_f32_32x32x16_bf16 v[96:111], v[84:87], v[140:143], v[96:111]
	s_waitcnt lgkmcnt(4)
	v_mfma_f32_32x32x16_bf16 v[112:127], v[204:207], v[140:143], v[112:127]
	buffer_load_dwordx4 v197, s[28:31], s11 offen lds
	v_add_f32_e32 v84, 0, v64
	v_add_f32_e32 v84, v65, v84
	v_add_f32_e32 v84, v66, v84
	v_add_f32_e32 v84, v67, v84
	v_add_f32_e32 v84, v226, v84
	v_add_f32_e32 v84, v227, v84
	v_add_f32_e32 v84, v228, v84
	v_add_f32_e32 v208, v229, v84
	s_mov_b32 m0, s49
	ds_read_b128 v[84:87], v230 offset:32896
	ds_read_b128 v[204:207], v230 offset:45184
	s_waitcnt lgkmcnt(5)
	v_mfma_f32_32x32x16_bf16 v[96:111], v[88:91], v[136:139], v[96:111]
	s_waitcnt lgkmcnt(4)
	v_mfma_f32_32x32x16_bf16 v[112:127], v[212:215], v[136:139], v[112:127]
	buffer_load_dwordx4 v198, s[28:31], s11 offen lds
	v_add_f32_e32 v88, v68, v208
	v_add_f32_e32 v88, v69, v88
	v_add_f32_e32 v88, v70, v88
	v_add_f32_e32 v88, v71, v88
	v_add_f32_e32 v88, v231, v88
	v_add_f32_e32 v88, v232, v88
	v_add_f32_e32 v88, v233, v88
	v_add_f32_e32 v212, v234, v88
	s_waitcnt lgkmcnt(3)
	v_mfma_f32_32x32x16_bf16 v[96:111], v[80:83], v[132:135], v[96:111]
	ds_read_b128 v[80:83], v203 offset:45312
	ds_read_b128 v[88:91], v203 offset:33024
	ds_read_b128 v[208:211], v192
	s_waitcnt lgkmcnt(5)
	v_mfma_f32_32x32x16_bf16 v[112:127], v[92:95], v[132:135], v[112:127]
	v_add_f32_e32 v92, v72, v212
	v_add_f32_e32 v92, v73, v92
	v_add_f32_e32 v92, v74, v92
	v_add_f32_e32 v92, v75, v92
	v_add_f32_e32 v92, v235, v92
	v_add_f32_e32 v92, v236, v92
	v_add_f32_e32 v92, v237, v92
	v_add_f32_e32 v203, v238, v92
	s_waitcnt lgkmcnt(4)
	v_mfma_f32_32x32x16_bf16 v[96:111], v[84:87], v[128:131], v[96:111]
	ds_read_b128 v[84:87], v224 offset:45312
	ds_read_b128 v[92:95], v224 offset:33024
	ds_read_b128 v[212:215], v192 offset:1024
	s_waitcnt lgkmcnt(6)
; template <int I> __device__ __forceinline__ void fs_chunk(f32x16& p0, f32x16& p1, float alpha, float& l_reg, SMState& st, bf16x8& pa0, bf16x8& pa1, bf16x8& pa2, bf16x8& pa3) {
;     ...
;   if constexpr (I < 4) {
; #pragma unroll
;     for (int r = 4 * I; r < 4 * I + 4; ++r) p1[r] = __builtin_amdgcn_exp2f(p1[r]);
;     if constexpr (I == 0) st.ps = 0.f;
;   } else if constexpr (I < 8) { constexpr int j = 4 * (I - 4);
; #pragma unroll
;     for (int r = j; r < j + 4; ++r) st.ps += p0[r];
; #pragma unroll
;     for (int r = j; r < j + 4; ++r) st.ps += p1[r];
;   } else if constexpr (I == 8) {
;     const float ps_ = st.ps;
;     auto rr = __builtin_amdgcn_permlane32_swap(__float_as_uint(ps_), __float_as_uint(ps_), false, false);
;     l_reg = l_reg * alpha + (__uint_as_float(rr[0]) + __uint_as_float(rr[1]));
;     PK4(p0, 0, pa0);
;   } else if constexpr (I == 9) { PK4(p0, 8, pa1); }
;   else if constexpr (I == 10) { PK4(p1, 0, pa2); }
;   else { PK4(p1, 8, pa3); }
;     ...
; }
; template <int I> __device__ __forceinline__ void ps_chunk(f32x16& p0, f32x16& p1, float& M, float& alpha, SMState& st) {
;   if constexpr (I == 0) { float m = p0[0];
; #pragma unroll
;     for (int r = 1; r < 16; ++r) m = fmaxf(m, p0[r]);
;     st.pmax = m;
;   } else if constexpr (I == 1) { float m = st.pmax;
; #pragma unroll
;     for (int r = 0; r < 16; ++r) m = fmaxf(m, p1[r]);
;     auto rr = __builtin_amdgcn_permlane32_swap(__float_as_uint(m), __float_as_uint(m), false, false);
;     st.pmax = fmaxf(__uint_as_float(rr[0]), __uint_as_float(rr[1]));
;   } else if constexpr (I == 2) {
;     alpha = 1.f;
;     if (__builtin_expect(!__all(st.pmax <= THR2), 0)) { const float d = fmaxf(st.pmax, 0.f); M += d; alpha = __builtin_amdgcn_exp2f(-d);
; #pragma unroll
;       for (int r = 0; r < 16; ++r) { p0[r] -= d; p1[r] -= d; } }
; #pragma unroll
;     for (int r = 0; r < 2; ++r) p0[r] = __builtin_amdgcn_exp2f(p0[r]);
;   } else if constexpr (I < 7) { constexpr int lo = 2 + 3 * (I - 3), hi_ = lo + 3;
; #pragma unroll
;     for (int r = lo; r < hi_; ++r) p0[r] = __builtin_amdgcn_exp2f(p0[r]);
;   } else {
; #pragma unroll
;     for (int r = 14; r < 16; ++r) p0[r] = __builtin_amdgcn_exp2f(p0[r]);
;   }
;   if constexpr (I >= 2) asm volatile("" : "+v"(p0), "+v"(p1));
; }
	v_mfma_f32_32x32x16_bf16 v[112:127], v[204:207], v[128:131], v[112:127]
	v_add_f32_e32 v203, v76, v203
	v_add_f32_e32 v203, v77, v203
	v_add_f32_e32 v203, v78, v203
	v_add_f32_e32 v203, v79, v203
	v_add_f32_e32 v203, v239, v203
	v_add_f32_e32 v203, v240, v203
	v_add_f32_e32 v203, v241, v203
	v_add_f32_e32 v203, v242, v203
	s_waitcnt lgkmcnt(3)
	v_mfma_f32_32x32x16_bf16 v[96:111], v[88:91], v[208:211], v[96:111]
	ds_read_b128 v[88:91], v225 offset:45312
	ds_read_b128 v[216:219], v225 offset:33024
	ds_read_b128 v[220:223], v192 offset:2048
	v_mfma_f32_32x32x16_bf16 v[112:127], v[80:83], v[208:211], v[112:127]
	v_mov_b32_e32 v204, v203
	v_cvt_pk_bf16_f32 v80, v64, v65
	v_cvt_pk_bf16_f32 v81, v66, v67
	v_cvt_pk_bf16_f32 v82, v68, v69
	v_cvt_pk_bf16_f32 v83, v70, v71
	v_permlane32_swap_b32_e32 v203, v204
	v_permlane32_swap_b32_e32 v80, v82
	v_permlane32_swap_b32_e32 v81, v83
	s_waitcnt lgkmcnt(3)
	v_mfma_f32_32x32x16_bf16 v[96:111], v[92:95], v[212:215], v[96:111]
	ds_read_b128 v[64:67], v192 offset:3072
	ds_read_b128 v[92:95], v230 offset:33024
	ds_read_b128 v[206:209], v230 offset:45312
	v_mfma_f32_32x32x16_bf16 v[112:127], v[84:87], v[212:215], v[112:127]
	v_cvt_pk_bf16_f32 v72, v72, v73
	v_cvt_pk_bf16_f32 v73, v74, v75
	v_cvt_pk_bf16_f32 v74, v76, v77
	v_cvt_pk_bf16_f32 v75, v78, v79
	s_nop 0
	v_permlane32_swap_b32_e32 v72, v74
	v_permlane32_swap_b32_e32 v73, v75
	s_waitcnt lgkmcnt(3)
	v_mfma_f32_32x32x16_bf16 v[96:111], v[216:219], v[220:223], v[96:111]
	v_mfma_f32_32x32x16_bf16 v[112:127], v[88:91], v[220:223], v[112:127]
	v_cvt_pk_bf16_f32 v68, v226, v227
	v_cvt_pk_bf16_f32 v69, v228, v229
	v_cvt_pk_bf16_f32 v70, v231, v232
	v_cvt_pk_bf16_f32 v71, v233, v234
	s_nop 0
	v_permlane32_swap_b32_e32 v68, v70
	v_permlane32_swap_b32_e32 v69, v71
	s_waitcnt lgkmcnt(1)
	v_mfma_f32_32x32x16_bf16 v[96:111], v[92:95], v[64:67], v[96:111]
	s_waitcnt lgkmcnt(0)
	v_mfma_f32_32x32x16_bf16 v[112:127], v[206:209], v[64:67], v[112:127]
	v_cvt_pk_bf16_f32 v64, v235, v236
	v_cvt_pk_bf16_f32 v65, v237, v238
	v_cvt_pk_bf16_f32 v66, v239, v240
	v_cvt_pk_bf16_f32 v67, v241, v242
	s_nop 0
	v_permlane32_swap_b32_e32 v64, v66
	v_permlane32_swap_b32_e32 v65, v67
	ds_read_b64_tr_b16 v[78:79], v188 offset:2048
	ds_read_b64_tr_b16 v[76:77], v188
	ds_read_b64_tr_b16 v[84:85], v188 offset:512
	ds_read_b64_tr_b16 v[88:89], v188 offset:1024
	ds_read_b64_tr_b16 v[92:93], v188 offset:1536
	ds_read_b64_tr_b16 v[86:87], v188 offset:2560
	ds_read_b64_tr_b16 v[90:91], v188 offset:3072
	ds_read_b64_tr_b16 v[94:95], v188 offset:3584
	s_waitcnt lgkmcnt(6)
	v_mfma_f32_32x32x16_bf16 v[0:15], v[80:83], v[76:79], v[0:15]
	s_waitcnt lgkmcnt(2)
	v_mfma_f32_32x32x16_bf16 v[48:63], v[80:83], v[84:87], v[48:63]
	v_max_f32_e32 v76, v97, v97
	v_max_f32_e32 v77, v96, v96
	v_max_f32_e32 v76, v77, v76
	v_max3_f32 v76, v76, v98, v99
	v_max3_f32 v76, v76, v100, v101
	v_max3_f32 v76, v76, v102, v103
	v_max3_f32 v76, v76, v104, v105
	v_max3_f32 v76, v76, v106, v107
	v_max3_f32 v76, v76, v108, v109
	v_max3_f32 v84, v76, v110, v111
	s_waitcnt lgkmcnt(1)
	v_mfma_f32_32x32x16_bf16 v[32:47], v[80:83], v[88:91], v[32:47]
	ds_read_b64_tr_b16 v[76:77], v188 offset:4096
	ds_read_b64_tr_b16 v[78:79], v188 offset:6144
	ds_read_b64_tr_b16 v[88:89], v188 offset:6656
	ds_read_b64_tr_b16 v[86:87], v188 offset:4608
	s_waitcnt lgkmcnt(4)
	v_mfma_f32_32x32x16_bf16 v[16:31], v[80:83], v[92:95], v[16:31]
	v_max3_f32 v80, v84, v112, v113
	v_max3_f32 v80, v80, v114, v115
	v_max3_f32 v80, v80, v116, v117
	v_max3_f32 v80, v80, v118, v119
	v_max3_f32 v80, v80, v120, v121
	v_max3_f32 v80, v80, v122, v123
	v_max3_f32 v80, v80, v124, v125
	v_max3_f32 v80, v80, v126, v127
	v_mov_b32_e32 v81, v80
	s_nop 1
	v_permlane32_swap_b32_e32 v80, v81
	v_max_f32_e32 v81, v81, v81
	v_max_f32_e32 v80, v80, v80
	v_max_f32_e32 v84, v80, v81
	s_waitcnt lgkmcnt(2)
	v_mfma_f32_32x32x16_bf16 v[0:15], v[72:75], v[76:79], v[0:15]
	ds_read_b64_tr_b16 v[80:81], v188 offset:5120
	ds_read_b64_tr_b16 v[82:83], v188 offset:7168
	ds_read_b64_tr_b16 v[78:79], v188 offset:7680
	ds_read_b64_tr_b16 v[76:77], v188 offset:5632
	s_waitcnt lgkmcnt(4)
	v_mfma_f32_32x32x16_bf16 v[48:63], v[72:75], v[86:89], v[48:63]
	v_cmp_ge_f32_e32 vcc, s67, v84
	s_cmp_eq_u64 vcc, exec
	s_cbranch_scc0 .LBB0_668
	v_mov_b32_e32 v206, 1.0

; #define SBAR() __builtin_amdgcn_sched_barrier(0)
; template <int P> __device__ __forceinline__ void dma_piece(const DmaCtx& c) {
;   if constexpr (P < 3) __builtin_amdgcn_raw_ptr_buffer_load_lds(c.srd, (lds_u32_t*)(c.kd + (c.wid + 8 * P) * 1024), 16, c.koff[P], c.gk, 0, 0);
;   else __builtin_amdgcn_raw_ptr_buffer_load_lds(c.srd, (lds_u32_t*)(c.vd + (c.wid + 8 * (P - 3)) * 1024), 16, c.voff[P - 3], c.gv, 0, 0);
; }
; template <int D0> __device__ __forceinline__ void h1_stage(f32x16& pc0, f32x16& pc1, f32x16& pp0, f32x16& pp1, float alP, float& l_reg, SMState& st, bf16x8& pa0, bf16x8& pa1, bf16x8& pa2, bf16x8& pa3, ...
;   bf16x8 m0, m1, mq;
;   if constexpr (D0 < 10) kq_load<D0 + 2>(m0, m1, mq, Ks, qr, qlds, kb);
;   pc0 = __builtin_amdgcn_mfma_f32_32x32x16_bf16(b0, q, pc0, 0, 0, 0);
;   pc1 = __builtin_amdgcn_mfma_f32_32x32x16_bf16(b1, q, pc1, 0, 0, 0);
;   if constexpr (D0 >= 1 && D0 <= 5) dma_piece<D0 - 1>(dc);
;   SBAR(); fs_chunk<D0>(pp0, pp1, alP, l_reg, st, pa0, pa1, pa2, pa3); SBAR();
;   if constexpr (D0 < 11) h1_stage<D0 + 1>(pc0, pc1, pp0, pp1, alP, l_reg, st, pa0, pa1, pa2, pa3, n0, n1, nq, m0, m1, mq, Ks, qr, qlds, kb, dc);
; }
.Lattn_m1:
	v_xor_b32_e32 v80, 0x80000000, v191
	v_mov_b32_e32 v81, v80
	v_mov_b32_e32 v82, v80
	v_mov_b32_e32 v83, v80
	v_mov_b32_e32 v84, v80
	v_mov_b32_e32 v85, v80
	v_mov_b32_e32 v86, v80
	v_mov_b32_e32 v87, v80
	v_mov_b32_e32 v88, v80
	v_mov_b32_e32 v89, v80
	v_mov_b32_e32 v90, v80
	v_mov_b32_e32 v91, v80
	v_mov_b32_e32 v92, v80
	v_mov_b32_e32 v93, v80
	v_mov_b32_e32 v94, v80
	v_mov_b32_e32 v95, v80
	v_add_u32_e32 v207, s53, v199
	v_add_u32_e32 v228, s53, v200
	s_waitcnt lgkmcnt(1)
	v_mfma_f32_32x32x16_bf16 v[64:79], v[208:211], v[156:159], v[80:95]
	s_add_i32 s10, s51, 0x42000
	s_add_i32 s11, s52, 1
	ds_read_b128 v[208:211], v207 offset:32768
	ds_read_b128 v[216:219], v207 offset:45056
	ds_read_b128 v[220:223], v228 offset:32768
	ds_read_b128 v[224:227], v228 offset:45056
	s_cmp_lg_u32 s52, 2
	s_cselect_b32 s73, s11, 0
	s_mul_i32 s11, s73, 0x6000
	s_waitcnt lgkmcnt(4)
	v_mfma_f32_32x32x16_bf16 v[80:95], v[212:215], v[156:159], v[80:95]
	s_add_i32 s52, s11, 0
	v_exp_f32_e32 v229, v112
	v_exp_f32_e32 v230, v113
	v_exp_f32_e32 v231, v114
	v_exp_f32_e32 v232, v115
	s_add_i32 s11, s52, s69
	v_add_u32_e32 v233, s53, v201
	s_add_i32 m0, s11, 0x8000
	ds_read_b128 v[112:115], v233 offset:32768
	ds_read_b128 v[212:215], v233 offset:45056
	s_waitcnt lgkmcnt(5)
	v_mfma_f32_32x32x16_bf16 v[64:79], v[208:211], v[152:155], v[64:79]
	s_waitcnt lgkmcnt(4)
	v_mfma_f32_32x32x16_bf16 v[80:95], v[216:219], v[152:155], v[80:95]
	buffer_load_dwordx4 v194, s[28:31], s10 offen lds
	v_exp_f32_e32 v234, v116
	v_exp_f32_e32 v235, v117
	v_exp_f32_e32 v236, v118
	v_exp_f32_e32 v237, v119
	s_add_i32 m0, s11, 0xa000
	ds_read_b128 v[116:119], v205 offset:32896
	ds_read_b128 v[208:211], v205 offset:45184
	s_waitcnt lgkmcnt(5)
	v_mfma_f32_32x32x16_bf16 v[64:79], v[220:223], v[148:151], v[64:79]
	s_waitcnt lgkmcnt(4)
	v_mfma_f32_32x32x16_bf16 v[80:95], v[224:227], v[148:151], v[80:95]
	buffer_load_dwordx4 v195, s[28:31], s10 offen lds
	v_exp_f32_e32 v238, v120
	v_exp_f32_e32 v239, v121
	v_exp_f32_e32 v240, v122
	v_exp_f32_e32 v241, v123
	s_add_i32 m0, s11, 0xc000
	ds_read_b128 v[120:123], v207 offset:32896
	ds_read_b128 v[216:219], v207 offset:45184
	s_waitcnt lgkmcnt(5)
	v_mfma_f32_32x32x16_bf16 v[64:79], v[112:115], v[144:147], v[64:79]
	s_waitcnt lgkmcnt(4)
	v_mfma_f32_32x32x16_bf16 v[80:95], v[212:215], v[144:147], v[80:95]
	buffer_load_dwordx4 v196, s[28:31], s10 offen lds
	v_exp_f32_e32 v242, v124
	v_exp_f32_e32 v243, v125
	v_exp_f32_e32 v244, v126
	v_exp_f32_e32 v245, v127
	s_mov_b32 m0, s70
	ds_read_b128 v[112:115], v228 offset:32896
	ds_read_b128 v[124:127], v228 offset:45184
	s_waitcnt lgkmcnt(5)
	v_mfma_f32_32x32x16_bf16 v[64:79], v[116:119], v[140:143], v[64:79]
	s_waitcnt lgkmcnt(4)
	v_mfma_f32_32x32x16_bf16 v[80:95], v[208:211], v[140:143], v[80:95]
	buffer_load_dwordx4 v197, s[28:31], s51 offen lds
	v_add_f32_e32 v116, 0, v96
	v_add_f32_e32 v116, v97, v116
	v_add_f32_e32 v116, v98, v116
	v_add_f32_e32 v116, v99, v116
	v_add_f32_e32 v116, v229, v116
	v_add_f32_e32 v116, v230, v116
	v_add_f32_e32 v116, v231, v116
	v_add_f32_e32 v212, v232, v116
	s_mov_b32 m0, s71
	ds_read_b128 v[116:119], v233 offset:32896
	ds_read_b128 v[208:211], v233 offset:45184
	s_waitcnt lgkmcnt(5)
	v_mfma_f32_32x32x16_bf16 v[64:79], v[120:123], v[136:139], v[64:79]
	s_waitcnt lgkmcnt(4)
	v_mfma_f32_32x32x16_bf16 v[80:95], v[216:219], v[136:139], v[80:95]
	buffer_load_dwordx4 v198, s[28:31], s51 offen lds
	v_add_f32_e32 v120, v100, v212
	v_add_f32_e32 v120, v101, v120
	v_add_f32_e32 v120, v102, v120
	v_add_f32_e32 v120, v103, v120
	v_add_f32_e32 v120, v234, v120
	v_add_f32_e32 v120, v235, v120
	v_add_f32_e32 v120, v236, v120
	v_add_f32_e32 v216, v237, v120
	s_waitcnt lgkmcnt(3)
	v_mfma_f32_32x32x16_bf16 v[64:79], v[112:115], v[132:135], v[64:79]
	ds_read_b128 v[112:115], v205 offset:45312
	ds_read_b128 v[120:123], v205 offset:33024
	ds_read_b128 v[212:215], v192
	s_waitcnt lgkmcnt(5)
	v_mfma_f32_32x32x16_bf16 v[80:95], v[124:127], v[132:135], v[80:95]
	v_add_f32_e32 v124, v104, v216
	v_add_f32_e32 v124, v105, v124
	v_add_f32_e32 v124, v106, v124
	v_add_f32_e32 v124, v107, v124
	v_add_f32_e32 v124, v238, v124
	v_add_f32_e32 v124, v239, v124
	v_add_f32_e32 v124, v240, v124
	v_add_f32_e32 v205, v241, v124
	s_waitcnt lgkmcnt(4)
	v_mfma_f32_32x32x16_bf16 v[64:79], v[116:119], v[128:131], v[64:79]
	ds_read_b128 v[124:127], v207 offset:45312
	ds_read_b128 v[216:219], v207 offset:33024
	ds_read_b128 v[220:223], v192 offset:1024
	s_waitcnt lgkmcnt(6)
; template <int I> __device__ __forceinline__ void fs_chunk(f32x16& p0, f32x16& p1, float alpha, float& l_reg, SMState& st, bf16x8& pa0, bf16x8& pa1, bf16x8& pa2, bf16x8& pa3) {
;     ...
;   if constexpr (I < 4) {
; #pragma unroll
;     for (int r = 4 * I; r < 4 * I + 4; ++r) p1[r] = __builtin_amdgcn_exp2f(p1[r]);
;     if constexpr (I == 0) st.ps = 0.f;
;   } else if constexpr (I < 8) { constexpr int j = 4 * (I - 4);
; #pragma unroll
;     for (int r = j; r < j + 4; ++r) st.ps += p0[r];
; #pragma unroll
;     for (int r = j; r < j + 4; ++r) st.ps += p1[r];
;   } else if constexpr (I == 8) {
;     const float ps_ = st.ps;
;     auto rr = __builtin_amdgcn_permlane32_swap(__float_as_uint(ps_), __float_as_uint(ps_), false, false);
;     l_reg = l_reg * alpha + (__uint_as_float(rr[0]) + __uint_as_float(rr[1]));
;     PK4(p0, 0, pa0);
;   } else if constexpr (I == 9) { PK4(p0, 8, pa1); }
;   else if constexpr (I == 10) { PK4(p1, 0, pa2); }
;   else { PK4(p1, 8, pa3); }
;     ...
; }
; template <int I> __device__ __forceinline__ void ps_chunk(f32x16& p0, f32x16& p1, float& M, float& alpha, SMState& st) {
;   if constexpr (I == 0) { float m = p0[0];
; #pragma unroll
;     for (int r = 1; r < 16; ++r) m = fmaxf(m, p0[r]);
;     st.pmax = m;
;   } else if constexpr (I == 1) { float m = st.pmax;
; #pragma unroll
;     for (int r = 0; r < 16; ++r) m = fmaxf(m, p1[r]);
;     auto rr = __builtin_amdgcn_permlane32_swap(__float_as_uint(m), __float_as_uint(m), false, false);
;     st.pmax = fmaxf(__uint_as_float(rr[0]), __uint_as_float(rr[1]));
;   } else if constexpr (I == 2) {
;     alpha = 1.f;
;     if (__builtin_expect(!__all(st.pmax <= THR2), 0)) { const float d = fmaxf(st.pmax, 0.f); M += d; alpha = __builtin_amdgcn_exp2f(-d);
; #pragma unroll
;       for (int r = 0; r < 16; ++r) { p0[r] -= d; p1[r] -= d; } }
; #pragma unroll
;     for (int r = 0; r < 2; ++r) p0[r] = __builtin_amdgcn_exp2f(p0[r]);
;   } else if constexpr (I < 7) { constexpr int lo = 2 + 3 * (I - 3), hi_ = lo + 3;
; #pragma unroll
;     for (int r = lo; r < hi_; ++r) p0[r] = __builtin_amdgcn_exp2f(p0[r]);
;   } else {
; #pragma unroll
;     for (int r = 14; r < 16; ++r) p0[r] = __builtin_amdgcn_exp2f(p0[r]);
;   }
;   if constexpr (I >= 2) asm volatile("" : "+v"(p0), "+v"(p1));
; }
	v_mfma_f32_32x32x16_bf16 v[80:95], v[208:211], v[128:131], v[80:95]
	v_add_f32_e32 v116, v108, v205
	v_add_f32_e32 v116, v109, v116
	v_add_f32_e32 v116, v110, v116
	v_add_f32_e32 v116, v111, v116
	v_add_f32_e32 v116, v242, v116
	v_add_f32_e32 v116, v243, v116
	v_add_f32_e32 v116, v244, v116
	v_add_f32_e32 v116, v245, v116
	s_waitcnt lgkmcnt(3)
	v_mfma_f32_32x32x16_bf16 v[64:79], v[120:123], v[212:215], v[64:79]
	ds_read_b128 v[118:121], v228 offset:45312
	ds_read_b128 v[208:211], v228 offset:33024
	ds_read_b128 v[224:227], v192 offset:2048
	v_mfma_f32_32x32x16_bf16 v[80:95], v[112:115], v[212:215], v[80:95]
	v_mov_b32_e32 v117, v116
	v_cvt_pk_bf16_f32 v112, v96, v97
	v_cvt_pk_bf16_f32 v113, v98, v99
	v_cvt_pk_bf16_f32 v114, v100, v101
	v_cvt_pk_bf16_f32 v115, v102, v103
	v_permlane32_swap_b32_e32 v116, v117
	v_permlane32_swap_b32_e32 v112, v114
	v_permlane32_swap_b32_e32 v113, v115
	s_waitcnt lgkmcnt(3)
	v_mfma_f32_32x32x16_bf16 v[64:79], v[216:219], v[220:223], v[64:79]
	ds_read_b128 v[96:99], v192 offset:3072
	ds_read_b128 v[212:215], v233 offset:33024
	ds_read_b128 v[216:219], v233 offset:45312
	v_mfma_f32_32x32x16_bf16 v[80:95], v[124:127], v[220:223], v[80:95]
	v_cvt_pk_bf16_f32 v104, v104, v105
	v_cvt_pk_bf16_f32 v105, v106, v107
	v_cvt_pk_bf16_f32 v106, v108, v109
	v_cvt_pk_bf16_f32 v107, v110, v111
	s_nop 0
	v_permlane32_swap_b32_e32 v104, v106
	v_permlane32_swap_b32_e32 v105, v107
	s_waitcnt lgkmcnt(3)
	v_mfma_f32_32x32x16_bf16 v[64:79], v[208:211], v[224:227], v[64:79]
	v_mfma_f32_32x32x16_bf16 v[80:95], v[118:121], v[224:227], v[80:95]
	v_cvt_pk_bf16_f32 v100, v229, v230
	v_cvt_pk_bf16_f32 v101, v231, v232
	v_cvt_pk_bf16_f32 v102, v234, v235
	v_cvt_pk_bf16_f32 v103, v236, v237
	s_nop 0
	v_permlane32_swap_b32_e32 v100, v102
	v_permlane32_swap_b32_e32 v101, v103
	s_waitcnt lgkmcnt(1)
	v_mfma_f32_32x32x16_bf16 v[64:79], v[212:215], v[96:99], v[64:79]
	s_waitcnt lgkmcnt(0)
	v_mfma_f32_32x32x16_bf16 v[80:95], v[216:219], v[96:99], v[80:95]
	v_cvt_pk_bf16_f32 v96, v238, v239
	v_cvt_pk_bf16_f32 v97, v240, v241
	v_cvt_pk_bf16_f32 v98, v242, v243
	v_cvt_pk_bf16_f32 v99, v244, v245
	s_nop 0
	v_permlane32_swap_b32_e32 v96, v98
	v_permlane32_swap_b32_e32 v97, v99
	ds_read_b64_tr_b16 v[110:111], v188 offset:18432
	ds_read_b64_tr_b16 v[108:109], v188 offset:16384
	ds_read_b64_tr_b16 v[118:119], v188 offset:16896
	ds_read_b64_tr_b16 v[122:123], v188 offset:17408
	ds_read_b64_tr_b16 v[208:209], v188 offset:17920
	ds_read_b64_tr_b16 v[120:121], v188 offset:18944
	ds_read_b64_tr_b16 v[124:125], v188 offset:19456
	ds_read_b64_tr_b16 v[210:211], v188 offset:19968
	s_waitcnt lgkmcnt(6)
	v_mfma_f32_32x32x16_bf16 v[0:15], v[112:115], v[108:111], v[0:15]
	s_waitcnt lgkmcnt(2)
	v_mfma_f32_32x32x16_bf16 v[48:63], v[112:115], v[118:121], v[48:63]
	v_max_f32_e32 v108, v65, v65
	v_max_f32_e32 v109, v64, v64
	v_max_f32_e32 v108, v109, v108
	v_max3_f32 v108, v108, v66, v67
	v_max3_f32 v108, v108, v68, v69
	v_max3_f32 v108, v108, v70, v71
	v_max3_f32 v108, v108, v72, v73
	v_max3_f32 v108, v108, v74, v75
	v_max3_f32 v108, v108, v76, v77
	v_max3_f32 v118, v108, v78, v79
	s_waitcnt lgkmcnt(1)
	v_mfma_f32_32x32x16_bf16 v[32:47], v[112:115], v[122:125], v[32:47]
	ds_read_b64_tr_b16 v[108:109], v188 offset:20480
	ds_read_b64_tr_b16 v[110:111], v188 offset:22528
	ds_read_b64_tr_b16 v[122:123], v188 offset:23040
	ds_read_b64_tr_b16 v[120:121], v188 offset:20992
	s_waitcnt lgkmcnt(4)
	v_mfma_f32_32x32x16_bf16 v[16:31], v[112:115], v[208:211], v[16:31]
	v_max3_f32 v112, v118, v80, v81
	v_max3_f32 v112, v112, v82, v83
	v_max3_f32 v112, v112, v84, v85
	v_max3_f32 v112, v112, v86, v87
	v_max3_f32 v112, v112, v88, v89
	v_max3_f32 v112, v112, v90, v91
	v_max3_f32 v112, v112, v92, v93
	v_max3_f32 v112, v112, v94, v95
	v_mov_b32_e32 v113, v112
	s_nop 1
	v_permlane32_swap_b32_e32 v112, v113
	v_max_f32_e32 v113, v113, v113
	v_max_f32_e32 v112, v112, v112
	v_max_f32_e32 v118, v112, v113
	s_waitcnt lgkmcnt(2)
	v_mfma_f32_32x32x16_bf16 v[0:15], v[104:107], v[108:111], v[0:15]
	ds_read_b64_tr_b16 v[112:113], v188 offset:21504
	ds_read_b64_tr_b16 v[114:115], v188 offset:23552
	ds_read_b64_tr_b16 v[110:111], v188 offset:24064
	ds_read_b64_tr_b16 v[108:109], v188 offset:22016
	s_waitcnt lgkmcnt(4)
	v_mfma_f32_32x32x16_bf16 v[48:63], v[104:107], v[120:123], v[48:63]
	v_cmp_ge_f32_e32 vcc, s67, v118
	s_cmp_eq_u64 vcc, exec
	v_mov_b32_e32 v205, 1.0
	s_cbranch_scc0 .LBB0_669
